# v17 + FFN-up EpiConvGate VALU trims: -log2e multiply folded into pre-scaled conv weights (exp with negated source), 24 halo selects done in place by bounded row-shift DPP
# baseline (speedup 1.0000x reference)
.LBB0_1152:
	v_readlane_b32 s14, v255, 4
	s_mov_b32 s24, s14
	s_mul_hi_u32 s1, s14, 0x21000
	s_mul_i32 s14, s14, 0x21000
	v_readlane_b32 s15, v255, 5
	s_add_u32 s86, s12, s14
	s_mul_hi_u32 s15, s24, 0xb000
	s_mul_i32 s24, s24, 0xb000
	s_addc_u32 s87, s13, s1
	v_and_b32_e32 v190, 15, v8
	v_bfe_u32 v19, v8, 4, 2
	s_add_u32 s38, s3, s24
	v_lshlrev_b32_e32 v21, 4, v19
	v_lshlrev_b32_e32 v22, 2, v190
	s_addc_u32 s39, s6, s15
	s_and_b32 s6, s0, 3
	v_lshl_or_b32 v21, v190, 6, v21
	s_lshl_b32 s0, s50, 13
	v_and_b32_e32 v23, 32, v22
	s_add_i32 m0, s17, 0x18000
	v_lshl_add_u64 v[0:1], v[0:1], 0, s[30:31]
	v_bitop3_b32 v24, v21, s0, v23 bitop3:0xde
	s_lshl_b32 s0, s6, 12
	s_waitcnt vmcnt(2)
	s_barrier
	global_load_lds_dwordx4 v[0:1], off
	v_lshl_add_u64 v[0:1], v[2:3], 0, s[30:31]
	s_add_i32 m0, s17, 0x1a000
	s_add_i32 s36, s17, 0x8000
	s_add_i32 s37, s17, 0xa000
	v_bitop3_b32 v191, v21, s0, v23 bitop3:0xde
	global_load_lds_dwordx4 v[0:1], off
	v_lshl_add_u64 v[0:1], v[4:5], 0, s[30:31]
	s_mov_b32 m0, s36
	s_add_u32 s0, s34, 0x80080
	global_load_lds_dwordx4 v[0:1], off
	v_lshl_add_u64 v[0:1], v[6:7], 0, s[30:31]
	s_mov_b32 m0, s37
	s_addc_u32 s1, s35, 0
	global_load_lds_dwordx4 v[0:1], off
	s_add_i32 m0, s17, 0x1c000
	v_lshl_add_u64 v[0:1], s[0:1], 0, v[96:97]
	global_load_lds_dwordx4 v[0:1], off
	v_lshl_add_u64 v[0:1], s[0:1], 0, v[182:183]
	s_add_i32 m0, s17, 0x1e000
	s_cmpk_gt_u32 s2, 0xff
	global_load_lds_dwordx4 v[0:1], off
	s_cselect_b64 s[72:73], -1, 0
	s_lshl_b32 s0, s50, 2
	s_or_b32 s3, s0, s6
	s_lshl_b32 s14, s3, 6
	s_cmp_lt_u32 s6, 2
	s_cselect_b32 s15, 0, 0x1600
	s_mov_b32 s101, 0x3f317218
	s_cmov_b32 s101, 0x3fb8aa3b
	s_nop 0
	s_nop 0
	s_nop 0
	s_nop 0
	s_nop 0
	s_nop 0
	s_nop 0
	s_nop 0
	s_nop 0
	s_nop 0
	s_nop 0
	s_nop 0
	s_cmp_lt_i32 s50, 3
	s_cselect_b64 s[0:1], -1, 0
	s_add_i32 s12, s14, 0x200
	s_ashr_i32 s48, s12, 8
	s_cmp_lt_i32 s48, 3
	v_cmp_eq_u32_e64 s[44:45], 15, v190
	v_or_b32_e32 v0, s50, v190
	s_cselect_b64 s[42:43], -1, 0
	s_and_b64 s[12:13], s[44:45], s[8:9]
	v_cmp_eq_u32_e64 s[46:47], 0, v0
	s_lshl_b32 s58, s3, 10
	s_nor_b64 s[96:97], s[46:47], s[12:13]
	s_or_b32 s51, s6, 4
	s_and_b64 s[12:13], s[8:9], exec
	s_cselect_b32 s3, s6, s51
	s_lshl_b32 s52, s3, 10
	s_cmpk_lt_u32 s2, 0x100
	s_cselect_b64 s[24:25], -1, 0
	v_and_b32_e32 v1, 63, v8
	v_mov_b32_e32 v3, 0x7f
	s_and_b64 s[2:3], s[24:25], exec
	v_or_b32_e32 v2, s14, v1
	v_bitop3_b32 v1, s14, v3, v1 bitop3:0xc8
	s_cselect_b32 s2, s51, s6
	s_cselect_b32 s3, 0, 0x200
	s_add_i32 s59, 0, 0x20400
	v_or_b32_e32 v192, s15, v1
	s_mul_hi_i32 s15, s48, 0xb000
	s_mul_i32 s14, s48, 0xb000
	v_cmp_eq_u32_e64 s[48:49], 0, v190
	v_mov_b32_e32 v1, 0x100
	s_add_i32 s74, s59, s58
	s_add_i32 s58, s58, 0
	v_lshlrev_b32_e32 v20, 3, v19
	v_cndmask_b32_e64 v0, 0, 1, s[8:9]
	v_cndmask_b32_e64 v1, v1, 0, s[48:49]
	v_lshlrev_b32_e32 v3, 6, v19
	s_add_i32 s58, s58, 0x20600
	v_lshlrev_b32_e32 v0, 9, v0
	v_lshl_or_b32 v193, s6, 5, v20
	s_lshl_b32 s2, s2, 10
	s_add_i32 s61, s59, s52
	v_add3_u32 v216, s58, v1, v3
	v_readlane_b32 s58, v254, 33
	s_lshl_b32 s6, s6, 7
	v_add_u32_e32 v0, s61, v0
	v_add3_u32 v215, s74, v1, v3
	v_lshl_add_u32 v217, v2, 2, s58
	s_add_i32 s58, s58, s6
	v_lshlrev_b32_e32 v1, 5, v19
	s_add_i32 s2, s59, s2
	s_add_i32 s59, s59, s6
	v_add_u32_e32 v218, s58, v1
	v_add_u32_e32 v0, 0xfffffe00, v0
	v_add_u32_e32 v223, s59, v1
	v_and_b32_e32 v1, 1, v9
	v_add_u32_e32 v219, v0, v3
	v_add3_u32 v0, v11, v12, v14
	v_lshlrev_b32_e32 v1, 6, v1
	s_add_i32 s3, s2, s3
	v_lshl_or_b32 v0, v0, 12, v1
	v_add_u32_e32 v220, s3, v3
	v_add_u32_e32 v222, s2, v3
	v_lshl_add_u32 v0, v10, 1, v0
	v_mov_b32_e32 v1, v97
	s_mov_b64 s[2:3], 0x80080
	v_lshl_add_u64 v[184:185], v[0:1], 0, s[2:3]
	v_and_b32_e32 v1, 1, v13
	v_add3_u32 v0, v16, v17, v18
	v_lshlrev_b32_e32 v1, 6, v1
	s_waitcnt vmcnt(6)
	v_lshl_or_b32 v0, v0, 12, v1
	v_lshl_or_b32 v194, s50, 6, v22
	s_movk_i32 s52, 0xfc
	s_movk_i32 s54, 0xff80
	s_movk_i32 s56, 0x7c
	s_add_i32 s61, s61, s23
	v_lshl_add_u32 v0, v15, 1, v0
	v_mov_b32_e32 v1, v97
	s_mul_hi_i32 s13, s50, 0xb000
	s_mul_i32 s12, s50, 0xb000
	v_add_u32_e32 v195, 0x82, v194
	v_add_u32_e32 v214, 0x83, v194
	v_cmp_ne_u32_e64 s[50:51], 0, v194
	v_cmp_ne_u32_e64 s[52:53], s52, v194
	v_cmp_ne_u32_e64 s[54:55], s54, v194
	v_cmp_ne_u32_e64 s[56:57], s56, v194
	v_add_u32_e32 v221, s61, v3
	v_lshl_add_u64 v[186:187], v[0:1], 0, s[2:3]
	v_add_u32_e32 v224, 0, v24
	s_barrier
	s_branch .LBB0_1155

.LBB0_1161:
	s_branch .Lmy_pad3
	s_nop 0
	s_nop 0
	s_nop 0
	s_nop 0
	s_nop 0
	s_nop 0
	s_nop 0
	s_nop 0
	s_nop 0
	s_nop 0
	s_nop 0
	s_nop 0
	s_nop 0
	s_nop 0
	s_nop 0
	s_nop 0
	s_nop 0
	s_nop 0
	s_nop 0
	s_nop 0
	s_nop 0
	s_nop 0
	s_nop 0
	s_nop 0
	s_nop 0

.LBB0_1165:
	s_or_b64 exec, exec, s[34:35]
	s_waitcnt vmcnt(0)
	v_mul_f32_e32 v238, s101, v238
	v_mul_f32_e32 v239, s101, v239
	ds_write2st64_b32 v217, v238, v239 offset1:8
	s_waitcnt vmcnt(0) lgkmcnt(0)
	s_barrier
	v_or_b32_e32 v188, s2, v193
	v_ashrrev_i32_e32 v189, 31, v188
	s_and_saveexec_b64 s[2:3], s[96:97]
	s_xor_b64 s[34:35], exec, s[2:3]
	s_andn2_saveexec_b64 s[34:35], s[34:35]
	s_cbranch_execz .LBB0_1167
	s_ashr_i32 s23, s22, 31
	v_readlane_b32 s60, v252, 48
	s_lshl_b64 s[2:3], s[22:23], 2
	v_cndmask_b32_e64 v130, 2, 0, s[46:47]
	v_readlane_b32 s61, v252, 49
	v_or_b32_e32 v132, s2, v130
	s_mov_b32 s2, 0xb000
	v_mov_b64_e32 v[130:131], s[60:61]
	v_mad_u64_u32 v[130:131], s[60:61], v132, s2, v[130:131]
	v_mov_b32_e32 v132, 0xb000
	v_mad_i32_i24 v131, s3, v132, v131
	v_lshl_add_u64 v[134:135], v[188:189], 2, v[130:131]
	v_cndmask_b32_e64 v133, v87, v129, s[46:47]
	v_cndmask_b32_e64 v132, v86, v128, s[46:47]
	v_cndmask_b32_e64 v131, v85, v127, s[46:47]
	v_cndmask_b32_e64 v130, v84, v126, s[46:47]
	v_add_co_u32_e32 v136, vcc, s2, v134
	global_store_dwordx4 v[134:135], v[130:133], off
	s_nop 0
	v_addc_co_u32_e32 v137, vcc, 0, v135, vcc
	v_cndmask_b32_e64 v133, v83, v125, s[46:47]
	v_cndmask_b32_e64 v132, v82, v124, s[46:47]
	v_cndmask_b32_e64 v131, v81, v123, s[46:47]
	v_cndmask_b32_e64 v130, v80, v122, s[46:47]
	global_store_dwordx4 v[136:137], v[130:133], off
	s_movk_i32 s2, 0x5000
	s_nop 0
	v_cndmask_b32_e64 v133, v19, v59, s[46:47]
	v_cndmask_b32_e64 v132, v18, v58, s[46:47]
	v_cndmask_b32_e64 v131, v17, v57, s[46:47]
	v_cndmask_b32_e64 v130, v16, v56, s[46:47]
	global_store_dwordx4 v[134:135], v[130:133], off offset:16
	s_nop 1
	v_cndmask_b32_e64 v133, v23, v55, s[46:47]
	v_cndmask_b32_e64 v132, v22, v54, s[46:47]
	v_cndmask_b32_e64 v131, v21, v53, s[46:47]
	v_cndmask_b32_e64 v130, v20, v52, s[46:47]
	global_store_dwordx4 v[136:137], v[130:133], off offset:16
	v_add_co_u32_e32 v136, vcc, s2, v134
	s_mov_b32 s2, 0x10000
	s_nop 0
	v_addc_co_u32_e32 v137, vcc, 0, v135, vcc
	v_cndmask_b32_e64 v133, v71, v113, s[46:47]
	v_cndmask_b32_e64 v132, v70, v112, s[46:47]
	v_cndmask_b32_e64 v131, v69, v111, s[46:47]
	v_cndmask_b32_e64 v130, v68, v110, s[46:47]
	v_add_co_u32_e32 v134, vcc, s2, v134
	global_store_dwordx4 v[136:137], v[130:133], off offset:2048
	s_nop 0
	v_addc_co_u32_e32 v135, vcc, 0, v135, vcc
	v_cndmask_b32_e64 v133, v67, v109, s[46:47]
	v_cndmask_b32_e64 v132, v66, v108, s[46:47]
	v_cndmask_b32_e64 v131, v65, v107, s[46:47]
	v_cndmask_b32_e64 v130, v64, v106, s[46:47]
	global_store_dwordx4 v[134:135], v[130:133], off offset:2048
	s_nop 1
	v_cndmask_b32_e64 v133, v3, v43, s[46:47]
	v_cndmask_b32_e64 v132, v2, v42, s[46:47]
	v_cndmask_b32_e64 v131, v1, v41, s[46:47]
	v_cndmask_b32_e64 v130, v0, v40, s[46:47]
	global_store_dwordx4 v[136:137], v[130:133], off offset:2064
	s_nop 1
	v_cndmask_b32_e64 v133, v7, v39, s[46:47]
	v_cndmask_b32_e64 v132, v6, v38, s[46:47]
	v_cndmask_b32_e64 v131, v5, v37, s[46:47]
	v_cndmask_b32_e64 v130, v4, v36, s[46:47]
	global_store_dwordx4 v[134:135], v[130:133], off offset:2064

.LBB0_1169:
	ds_read_b128 v[166:169], v220
	v_mov_b32_dpp v225, v128 row_ror:15 row_mask:0xf bank_mask:0xf
	v_mov_b32_dpp v226, v129 row_ror:15 row_mask:0xf bank_mask:0xf
	ds_read_b128 v[138:141], v218 offset:512
	ds_read_b128 v[142:145], v218 offset:1536
	ds_read_b128 v[134:137], v218 offset:2560
	ds_read_b128 v[130:133], v218 offset:3584
	s_movk_i32 s2, 0x200
	s_and_b64 vcc, exec, s[62:63]
	v_mov_b32_e32 v147, 0
	v_mov_b32_e32 v148, 0
	v_mov_b32_e32 v149, 0
	s_cbranch_vccnz .LBB0_1171
	ds_read_b128 v[146:149], v219 offset:288
	s_movk_i32 s2, 0x400
.LBB0_1171:
	s_waitcnt lgkmcnt(5)
	v_mov_b32_dpp v170, v114 row_shr:1 row_mask:0xf bank_mask:0xf
	v_mov_b32_dpp v171, v115 row_shr:1 row_mask:0xf bank_mask:0xf
	v_pk_fma_f32 v[170:171], v[150:151], v[170:171], v[158:159]
	v_pk_fma_f32 v[202:203], v[118:119], v[162:163], v[158:159]
	v_pk_fma_f32 v[170:171], v[126:127], v[162:163], v[170:171]
	v_pk_fma_f32 v[198:199], v[122:123], v[162:163], v[158:159]
	v_pk_fma_f32 v[170:171], v[122:123], v[154:155], v[170:171]
	v_pk_fma_f32 v[122:123], v[122:123], v[150:151], v[202:203]
	s_waitcnt lgkmcnt(4)
	v_mov_b32_dpp v167, v127 row_shl:1 row_mask:0xf bank_mask:0xf
	v_pk_fma_f32 v[122:123], v[114:115], v[154:155], v[122:123]
	v_pk_mul_f32 v[114:115], v[114:115], v[162:163]
	v_mov_b32_dpp v166, v126 row_shl:1 row_mask:0xf bank_mask:0xf
	v_pk_fma_f32 v[114:115], v[118:119], v[150:151], v[114:115]
	v_pk_fma_f32 v[126:127], v[126:127], v[150:151], v[198:199]
	v_pk_fma_f32 v[114:115], v[154:155], v[166:167], v[114:115]
	v_pk_fma_f32 v[126:127], v[118:119], v[154:155], v[126:127]
	v_pk_add_f32 v[118:119], v[158:159], v[114:115]
	v_mov_b32_dpp v172, v116 row_shr:1 row_mask:0xf bank_mask:0xf
	v_mov_b32_dpp v173, v117 row_shr:1 row_mask:0xf bank_mask:0xf
	v_exp_f32_e64 v114, -v118
	v_pk_fma_f32 v[172:173], v[152:153], v[172:173], v[160:161]
	v_exp_f32_e64 v115, -v119
	v_pk_fma_f32 v[172:173], v[128:129], v[164:165], v[172:173]
	v_pk_fma_f32 v[204:205], v[120:121], v[164:165], v[160:161]
	v_pk_fma_f32 v[172:173], v[124:125], v[156:157], v[172:173]
	v_pk_fma_f32 v[200:201], v[124:125], v[164:165], v[160:161]
	v_pk_fma_f32 v[124:125], v[124:125], v[152:153], v[204:205]
	v_add_f32_e32 v114, 1.0, v114
	v_pk_fma_f32 v[124:125], v[116:117], v[156:157], v[124:125]
	v_pk_mul_f32 v[116:117], v[116:117], v[164:165]
	v_rcp_f32_e32 v150, v114
	v_add_f32_e32 v151, 1.0, v115
	v_cndmask_b32_e64 v115, v226, v169, s[44:45]
	v_cndmask_b32_e64 v114, v225, v168, s[44:45]
	v_pk_fma_f32 v[116:117], v[120:121], v[152:153], v[116:117]
	v_pk_fma_f32 v[128:129], v[128:129], v[152:153], v[200:201]
	v_pk_fma_f32 v[114:115], v[156:157], v[114:115], v[116:117]
	v_pk_fma_f32 v[128:129], v[120:121], v[156:157], v[128:129]
	v_pk_add_f32 v[120:121], v[160:161], v[114:115]
	v_exp_f32_e64 v114, -v120
	v_exp_f32_e64 v115, -v121
	v_add_f32_e32 v114, 1.0, v114
	v_rcp_f32_e32 v152, v114
	v_add_f32_e32 v114, 1.0, v115
	v_rcp_f32_e32 v153, v114
	ds_read_b128 v[114:117], v220 offset:32
	v_mov_b32_dpp v155, v110 row_ror:15 row_mask:0xf bank_mask:0xf
	s_waitcnt lgkmcnt(1)
	v_mov_b32_dpp v146, v98 row_shr:1 row_mask:0xf bank_mask:0xf
	s_waitcnt lgkmcnt(0)
	v_cndmask_b32_e64 v154, v155, v114, s[44:45]
	v_exp_f32_e64 v178, -v170
	v_exp_f32_e64 v179, -v171
	v_exp_f32_e64 v180, -v172
	v_exp_f32_e64 v181, -v173
	v_mov_b32_dpp v155, v111 row_ror:15 row_mask:0xf bank_mask:0xf
	v_cndmask_b32_e64 v155, v155, v115, s[44:45]
	v_mov_b32_dpp v147, v99 row_shr:1 row_mask:0xf bank_mask:0xf
	v_mov_b32_dpp v116, v112 row_shl:1 row_mask:0xf bank_mask:0xf
	v_add_f32_e32 v178, 1.0, v178
	v_add_f32_e32 v179, 1.0, v179
	v_add_f32_e32 v180, 1.0, v180
	v_add_f32_e32 v181, 1.0, v181
	v_exp_f32_e64 v198, -v126
	v_exp_f32_e64 v199, -v127
	v_exp_f32_e64 v200, -v128
	v_exp_f32_e64 v201, -v129
	v_mov_b32_dpp v114, v100 row_ror:1 row_mask:0xf bank_mask:0xf
	v_mov_b32_dpp v115, v101 row_ror:1 row_mask:0xf bank_mask:0xf
	v_rcp_f32_e32 v178, v178
	v_rcp_f32_e32 v179, v179
	v_rcp_f32_e32 v180, v180
	v_rcp_f32_e32 v181, v181
	v_cndmask_b32_e64 v114, v114, v148, s[48:49]
	v_cndmask_b32_e64 v115, v115, v149, s[48:49]
	v_pk_fma_f32 v[114:115], v[140:141], v[114:115], v[132:133]
	v_pk_fma_f32 v[146:147], v[138:139], v[146:147], v[130:131]
	v_pk_fma_f32 v[146:147], v[110:111], v[142:143], v[146:147]
	v_pk_fma_f32 v[114:115], v[112:113], v[144:145], v[114:115]
	v_add_f32_e32 v198, 1.0, v198
	v_add_f32_e32 v199, 1.0, v199
	v_add_f32_e32 v200, 1.0, v200
	v_add_f32_e32 v201, 1.0, v201
	v_pk_fma_f32 v[114:115], v[108:109], v[136:137], v[114:115]
	v_pk_fma_f32 v[146:147], v[106:107], v[134:135], v[146:147]
	v_rcp_f32_e32 v198, v198
	v_rcp_f32_e32 v199, v199
	v_rcp_f32_e32 v200, v200
	v_rcp_f32_e32 v201, v201
	v_mov_b32_dpp v117, v113 row_shl:1 row_mask:0xf bank_mask:0xf
	v_pk_mul_f32 v[148:149], v[170:171], v[178:179]
	v_pk_mul_f32 v[156:157], v[172:173], v[180:181]
	v_exp_f32_e64 v202, -v122
	v_exp_f32_e64 v203, -v123
	v_pk_mul_f32 v[156:157], v[156:157], v[114:115]
	v_pk_mul_f32 v[114:115], v[148:149], v[146:147]
	v_pk_fma_f32 v[146:147], v[108:109], v[144:145], v[132:133]
	v_pk_fma_f32 v[148:149], v[106:107], v[142:143], v[130:131]
	v_exp_f32_e64 v204, -v124
	v_exp_f32_e64 v205, -v125
	v_pk_fma_f32 v[112:113], v[112:113], v[140:141], v[146:147]
	v_pk_fma_f32 v[110:111], v[110:111], v[138:139], v[148:149]
	v_pk_fma_f32 v[112:113], v[104:105], v[136:137], v[112:113]
	v_pk_fma_f32 v[110:111], v[102:103], v[134:135], v[110:111]
	v_pk_mul_f32 v[126:127], v[126:127], v[198:199]
	v_pk_mul_f32 v[128:129], v[128:129], v[200:201]
	v_add_f32_e32 v202, 1.0, v202
	v_add_f32_e32 v203, 1.0, v203
	v_pk_mul_f32 v[112:113], v[128:129], v[112:113]
	v_pk_mul_f32 v[110:111], v[126:127], v[110:111]
	v_pk_fma_f32 v[126:127], v[102:103], v[142:143], v[130:131]
	v_rcp_f32_e32 v202, v202
	v_rcp_f32_e32 v203, v203
	v_add_f32_e32 v204, 1.0, v204
	v_add_f32_e32 v205, 1.0, v205
	v_rcp_f32_e32 v151, v151
	v_cvt_pk_bf16_f32 v114, v114, v115
	v_cvt_pk_bf16_f32 v115, v156, v157
	v_cvt_pk_bf16_f32 v110, v110, v111
	v_cvt_pk_bf16_f32 v111, v112, v113
	v_pk_fma_f32 v[112:113], v[104:105], v[144:145], v[132:133]
	v_pk_fma_f32 v[106:107], v[106:107], v[138:139], v[126:127]
	v_rcp_f32_e32 v204, v204
	v_rcp_f32_e32 v205, v205
	v_pk_fma_f32 v[108:109], v[108:109], v[140:141], v[112:113]
	v_pk_fma_f32 v[106:107], v[98:99], v[134:135], v[106:107]
	v_pk_fma_f32 v[98:99], v[98:99], v[142:143], v[130:131]
	v_pk_fma_f32 v[108:109], v[100:101], v[136:137], v[108:109]
	v_pk_fma_f32 v[100:101], v[100:101], v[144:145], v[132:133]
	v_pk_fma_f32 v[98:99], v[102:103], v[138:139], v[98:99]
	v_pk_fma_f32 v[100:101], v[104:105], v[140:141], v[100:101]
	v_pk_fma_f32 v[98:99], v[134:135], v[154:155], v[98:99]
	v_pk_mul_f32 v[112:113], v[122:123], v[202:203]
	v_pk_fma_f32 v[100:101], v[136:137], v[116:117], v[100:101]
	v_pk_mul_f32 v[102:103], v[118:119], v[150:151]
	v_pk_mul_f32 v[122:123], v[124:125], v[204:205]
	v_pk_mul_f32 v[106:107], v[112:113], v[106:107]
	v_pk_mul_f32 v[104:105], v[120:121], v[152:153]
	v_pk_mul_f32 v[98:99], v[102:103], v[98:99]
	v_pk_mul_f32 v[108:109], v[122:123], v[108:109]
	v_cvt_pk_bf16_f32 v106, v106, v107
	v_pk_mul_f32 v[100:101], v[104:105], v[100:101]
	v_cvt_pk_bf16_f32 v107, v108, v109
	v_cvt_pk_bf16_f32 v98, v98, v99
	v_mov_b32_e32 v128, 0
	v_cvt_pk_bf16_f32 v99, v100, v101
	ds_read_b128 v[132:135], v218
	ds_read_b128 v[144:147], v218 offset:1024
	ds_read_b128 v[136:139], v218 offset:2048
	ds_read_b128 v[140:143], v218 offset:3072
	ds_read_b128 v[156:159], v221 offset:256
	v_cndmask_b32_e64 v100, 0, 1, s[10:11]
	v_cmp_ne_u32_e64 s[60:61], 1, v100
	s_andn2_b64 vcc, exec, s[10:11]
	v_add_u32_e32 v104, s2, v222
	v_mov_b32_e32 v152, 0
	v_mov_b32_e32 v153, 0
	v_mov_b32_e32 v154, 0
	v_mov_b32_e32 v155, 0
	s_cbranch_vccnz .LBB0_1173
	ds_read_b128 v[152:155], v104
.LBB0_1173:
	v_mov_b32_dpp v109, v92 row_ror:15 row_mask:0xf bank_mask:0xf
	v_mov_b32_dpp v112, v93 row_ror:15 row_mask:0xf bank_mask:0xf
	v_mov_b32_dpp v105, v94 row_ror:15 row_mask:0xf bank_mask:0xf
	v_mov_b32_dpp v108, v95 row_ror:15 row_mask:0xf bank_mask:0xf
	ds_read_b128 v[120:123], v218 offset:512
	ds_read_b128 v[124:127], v218 offset:1536
	ds_read_b128 v[116:119], v218 offset:2560
	ds_read_b128 v[100:103], v218 offset:3584
	ds_read_b128 v[148:151], v221 offset:288
	s_and_b64 vcc, exec, s[60:61]
	v_mov_b32_e32 v129, 0
	v_mov_b32_e32 v130, 0
	v_mov_b32_e32 v131, 0
	s_cbranch_vccnz .LBB0_1175
	ds_read_b128 v[128:131], v104 offset:32
.LBB0_1175:
	s_waitcnt lgkmcnt(5)
	v_mov_b32_dpp v159, v83 row_shr:1 row_mask:0xf bank_mask:0xf
	v_mov_b32_dpp v158, v82 row_shr:1 row_mask:0xf bank_mask:0xf
	v_pk_fma_f32 v[158:159], v[134:135], v[158:159], v[142:143]
	v_mov_b32_dpp v157, v81 row_shr:1 row_mask:0xf bank_mask:0xf
	v_pk_fma_f32 v[158:159], v[94:95], v[146:147], v[158:159]
	v_mov_b32_dpp v156, v80 row_shr:1 row_mask:0xf bank_mask:0xf
	v_pk_fma_f32 v[158:159], v[90:91], v[138:139], v[158:159]
	v_pk_fma_f32 v[156:157], v[132:133], v[156:157], v[140:141]
	v_pk_fma_f32 v[156:157], v[92:93], v[144:145], v[156:157]
	v_pk_fma_f32 v[156:157], v[88:89], v[136:137], v[156:157]
	v_exp_f32_e64 v113, -v158
	v_exp_f32_e64 v164, -v159
	v_exp_f32_e64 v161, -v156
	v_exp_f32_e64 v163, -v157
	v_add_f32_e32 v113, 1.0, v113
	v_rcp_f32_e32 v160, v113
	v_add_f32_e32 v113, 1.0, v164
	v_pk_fma_f32 v[164:165], v[88:89], v[144:145], v[140:141]
	v_add_f32_e32 v161, 1.0, v161
	v_pk_fma_f32 v[92:93], v[92:93], v[132:133], v[164:165]
	v_rcp_f32_e32 v162, v161
	v_pk_fma_f32 v[92:93], v[84:85], v[136:137], v[92:93]
	v_add_f32_e32 v161, 1.0, v163
	v_rcp_f32_e32 v163, v161
	v_exp_f32_e64 v164, -v92
	v_exp_f32_e64 v165, -v93
	v_pk_fma_f32 v[166:167], v[90:91], v[146:147], v[142:143]
	v_pk_fma_f32 v[168:169], v[84:85], v[144:145], v[140:141]
	v_pk_fma_f32 v[94:95], v[94:95], v[134:135], v[166:167]
	v_rcp_f32_e32 v161, v113
	v_pk_fma_f32 v[94:95], v[86:87], v[138:139], v[94:95]
	v_add_f32_e32 v113, 1.0, v164
	v_pk_fma_f32 v[88:89], v[88:89], v[132:133], v[168:169]
	v_rcp_f32_e32 v164, v113
	v_add_f32_e32 v113, 1.0, v165
	v_pk_fma_f32 v[88:89], v[80:81], v[136:137], v[88:89]
	v_pk_fma_f32 v[80:81], v[80:81], v[144:145], v[140:141]
	v_exp_f32_e64 v166, -v94
	v_cndmask_b32_e64 v152, v109, v152, s[44:45]
	v_cndmask_b32_e64 v153, v112, v153, s[44:45]
	v_pk_fma_f32 v[80:81], v[84:85], v[132:133], v[80:81]
	v_exp_f32_e64 v167, -v95
	v_pk_fma_f32 v[84:85], v[136:137], v[152:153], v[80:81]
	v_rcp_f32_e32 v165, v113
	v_add_f32_e32 v113, 1.0, v166
	v_exp_f32_e64 v80, -v84
	v_rcp_f32_e32 v166, v113
	v_add_f32_e32 v113, 1.0, v167
	v_exp_f32_e64 v81, -v85
	v_exp_f32_e64 v168, -v88
	v_pk_fma_f32 v[170:171], v[86:87], v[146:147], v[142:143]
	v_exp_f32_e64 v169, -v89
	v_pk_fma_f32 v[90:91], v[90:91], v[134:135], v[170:171]
	v_add_f32_e32 v80, 1.0, v80
	v_pk_fma_f32 v[90:91], v[82:83], v[138:139], v[90:91]
	v_pk_fma_f32 v[82:83], v[82:83], v[146:147], v[142:143]
	v_rcp_f32_e32 v112, v80
	v_add_f32_e32 v109, 1.0, v81
	v_cndmask_b32_e64 v80, v105, v154, s[44:45]
	v_cndmask_b32_e64 v81, v108, v155, s[44:45]
	v_pk_fma_f32 v[82:83], v[86:87], v[134:135], v[82:83]
	v_rcp_f32_e32 v167, v113
	v_add_f32_e32 v113, 1.0, v168
	v_pk_fma_f32 v[82:83], v[138:139], v[80:81], v[82:83]
	v_rcp_f32_e32 v168, v113
	v_add_f32_e32 v113, 1.0, v169
	v_exp_f32_e64 v170, -v90
	v_exp_f32_e64 v171, -v91
	v_exp_f32_e64 v80, -v82
	v_exp_f32_e64 v81, -v83
	v_rcp_f32_e32 v169, v113
	v_add_f32_e32 v113, 1.0, v170
	v_rcp_f32_e32 v170, v113
	v_add_f32_e32 v113, 1.0, v171
	v_add_f32_e32 v80, 1.0, v80
	v_mov_b32_dpp v105, v77 row_ror:15 row_mask:0xf bank_mask:0xf
	v_rcp_f32_e32 v171, v113
	v_rcp_f32_e32 v113, v109
	v_rcp_f32_e32 v86, v80
	v_add_f32_e32 v80, 1.0, v81
	s_waitcnt lgkmcnt(0)
	v_cndmask_b32_e64 v109, v105, v129, s[44:45]
	v_mov_b32_dpp v81, v76 row_ror:15 row_mask:0xf bank_mask:0xf
	v_rcp_f32_e32 v87, v80
	v_mov_b32_dpp v105, v66 row_ror:1 row_mask:0xf bank_mask:0xf
	v_cndmask_b32_e64 v108, v81, v128, s[44:45]
	v_cndmask_b32_e64 v128, v105, v150, s[48:49]
	v_mov_b32_dpp v80, v64 row_ror:1 row_mask:0xf bank_mask:0xf
	v_mov_b32_dpp v81, v65 row_ror:1 row_mask:0xf bank_mask:0xf
	v_mov_b32_dpp v105, v67 row_ror:1 row_mask:0xf bank_mask:0xf
	v_cndmask_b32_e64 v80, v80, v148, s[48:49]
	v_cndmask_b32_e64 v81, v81, v149, s[48:49]
	v_mov_b32_dpp v130, v78 row_shl:1 row_mask:0xf bank_mask:0xf
	v_cndmask_b32_e64 v129, v105, v151, s[48:49]
	v_pk_fma_f32 v[128:129], v[122:123], v[128:129], v[102:103]
	v_pk_fma_f32 v[80:81], v[120:121], v[80:81], v[100:101]
	v_pk_fma_f32 v[80:81], v[76:77], v[124:125], v[80:81]
	v_pk_fma_f32 v[128:129], v[78:79], v[126:127], v[128:129]
	v_pk_fma_f32 v[128:129], v[74:75], v[118:119], v[128:129]
	v_pk_fma_f32 v[80:81], v[72:73], v[116:117], v[80:81]
	v_mov_b32_dpp v131, v79 row_shl:1 row_mask:0xf bank_mask:0xf
	v_pk_mul_f32 v[132:133], v[156:157], v[162:163]
	v_pk_mul_f32 v[134:135], v[158:159], v[160:161]
	v_pk_mul_f32 v[80:81], v[132:133], v[80:81]
	v_pk_mul_f32 v[128:129], v[134:135], v[128:129]
	v_cvt_pk_bf16_f32 v80, v80, v81
	v_pk_fma_f32 v[132:133], v[72:73], v[124:125], v[100:101]
	v_cvt_pk_bf16_f32 v81, v128, v129
	v_pk_fma_f32 v[128:129], v[74:75], v[126:127], v[102:103]
	v_pk_fma_f32 v[76:77], v[76:77], v[120:121], v[132:133]
	v_pk_fma_f32 v[78:79], v[78:79], v[122:123], v[128:129]
	v_pk_fma_f32 v[76:77], v[68:69], v[116:117], v[76:77]
	v_pk_fma_f32 v[78:79], v[70:71], v[118:119], v[78:79]
	v_pk_mul_f32 v[92:93], v[92:93], v[164:165]
	v_pk_mul_f32 v[94:95], v[94:95], v[166:167]
	v_pk_mul_f32 v[76:77], v[92:93], v[76:77]
	v_pk_mul_f32 v[78:79], v[94:95], v[78:79]
	v_pk_fma_f32 v[92:93], v[68:69], v[124:125], v[100:101]
	v_cvt_pk_bf16_f32 v76, v76, v77
	v_cvt_pk_bf16_f32 v77, v78, v79
	v_pk_fma_f32 v[78:79], v[70:71], v[126:127], v[102:103]
	v_pk_fma_f32 v[72:73], v[72:73], v[120:121], v[92:93]
	v_pk_fma_f32 v[74:75], v[74:75], v[122:123], v[78:79]
	v_pk_fma_f32 v[72:73], v[64:65], v[116:117], v[72:73]
	v_pk_fma_f32 v[64:65], v[64:65], v[124:125], v[100:101]
	v_pk_fma_f32 v[74:75], v[66:67], v[118:119], v[74:75]
	v_pk_fma_f32 v[66:67], v[66:67], v[126:127], v[102:103]
	v_pk_fma_f32 v[64:65], v[68:69], v[120:121], v[64:65]
	v_pk_fma_f32 v[66:67], v[70:71], v[122:123], v[66:67]
	v_pk_fma_f32 v[64:65], v[116:117], v[108:109], v[64:65]
	v_pk_mul_f32 v[78:79], v[88:89], v[168:169]
	v_pk_fma_f32 v[66:67], v[118:119], v[130:131], v[66:67]
	v_pk_mul_f32 v[68:69], v[84:85], v[112:113]
	v_pk_mul_f32 v[88:89], v[90:91], v[170:171]
	v_pk_mul_f32 v[72:73], v[78:79], v[72:73]
	v_pk_mul_f32 v[70:71], v[82:83], v[86:87]
	v_pk_mul_f32 v[64:65], v[68:69], v[64:65]
	v_pk_mul_f32 v[74:75], v[88:89], v[74:75]
	v_cvt_pk_bf16_f32 v72, v72, v73
	v_pk_mul_f32 v[66:67], v[70:71], v[66:67]
	v_cvt_pk_bf16_f32 v73, v74, v75
	v_cvt_pk_bf16_f32 v64, v64, v65
	v_mov_b32_e32 v134, 0
	v_cvt_pk_bf16_f32 v65, v66, v67
	ds_read_b128 v[100:103], v223 offset:8208
	ds_read_b128 v[126:129], v223 offset:9232
	ds_read_b128 v[118:121], v223 offset:10256
	ds_read_b128 v[122:125], v223 offset:11280
	s_and_b64 vcc, exec, s[62:63]
	v_mov_b32_e32 v138, 0
	v_mov_b32_e32 v139, 0
	v_mov_b32_e32 v140, 0
	v_mov_b32_e32 v141, 0
	s_cbranch_vccnz .LBB0_1177
	ds_read_b128 v[138:141], v219 offset:272

.LBB0_1179:
	s_waitcnt lgkmcnt(5)
	v_cndmask_b32_e64 v78, v78, v140, s[48:49]
	v_cndmask_b32_e64 v79, v79, v141, s[48:49]
	v_pk_fma_f32 v[78:79], v[102:103], v[78:79], v[124:125]
	v_cndmask_b32_e64 v94, v94, v138, s[48:49]
	v_pk_fma_f32 v[78:79], v[58:59], v[128:129], v[78:79]
	v_cndmask_b32_e64 v95, v95, v139, s[48:49]
	v_pk_fma_f32 v[116:117], v[54:55], v[120:121], v[78:79]
	v_pk_fma_f32 v[94:95], v[100:101], v[94:95], v[122:123]
	v_pk_fma_f32 v[94:95], v[56:57], v[126:127], v[94:95]
	v_exp_f32_e64 v78, -v116
	v_exp_f32_e64 v79, -v117
	v_pk_fma_f32 v[108:109], v[52:53], v[118:119], v[94:95]
	v_add_f32_e32 v78, 1.0, v78
	v_rcp_f32_e32 v142, v78
	v_exp_f32_e64 v94, -v108
	v_add_f32_e32 v78, 1.0, v79
	v_exp_f32_e64 v95, -v109
	v_add_f32_e32 v94, 1.0, v94
	s_waitcnt lgkmcnt(0)
	v_mov_b32_dpp v134, v32 row_shr:1 row_mask:0xf bank_mask:0xf
	v_rcp_f32_e32 v112, v94
	v_mov_b32_dpp v135, v33 row_shr:1 row_mask:0xf bank_mask:0xf
	v_add_f32_e32 v94, 1.0, v95
	v_rcp_f32_e32 v113, v94
	v_rcp_f32_e32 v143, v78
	ds_read_b128 v[138:141], v220 offset:48
	v_mov_b32_dpp v136, v34 row_shr:1 row_mask:0xf bank_mask:0xf
	v_mov_b32_dpp v137, v35 row_shr:1 row_mask:0xf bank_mask:0xf
	v_pk_fma_f32 v[136:137], v[88:89], v[136:137], v[68:69]
	v_pk_fma_f32 v[134:135], v[86:87], v[134:135], v[66:67]
	v_pk_fma_f32 v[136:137], v[42:43], v[92:93], v[136:137]
	v_pk_fma_f32 v[134:135], v[40:41], v[90:91], v[134:135]
	v_pk_fma_f32 v[136:137], v[38:39], v[84:85], v[136:137]
	v_pk_fma_f32 v[134:135], v[36:37], v[82:83], v[134:135]
	s_lshl_b32 s2, s22, 8
	v_mov_b32_dpp v78, v40 row_ror:15 row_mask:0xf bank_mask:0xf
	v_mov_b32_dpp v94, v41 row_ror:15 row_mask:0xf bank_mask:0xf
	v_mov_b32_dpp v95, v42 row_ror:15 row_mask:0xf bank_mask:0xf
	v_mov_b32_dpp v79, v43 row_ror:15 row_mask:0xf bank_mask:0xf
	v_pk_mul_f32 v[108:109], v[108:109], v[112:113]
	v_pk_mul_f32 v[112:113], v[116:117], v[142:143]
	v_pk_mul_f32 v[108:109], v[108:109], v[134:135]
	v_pk_mul_f32 v[112:113], v[112:113], v[136:137]
	v_cvt_pk_bf16_f32 v116, v108, v109
	s_nop 0
	v_cvt_pk_bf16_f32 v117, v112, v113
	s_and_saveexec_b64 s[22:23], s[50:51]
	s_movk_i32 s3, 0x2c00
	s_cbranch_execz .LBB0_1181
	v_add_u32_e32 v105, s2, v194
	v_mov_b64_e32 v[108:109], s[88:89]
	v_mad_i64_i32 v[108:109], s[34:35], v105, s3, v[108:109]
	v_lshl_add_u64 v[108:109], v[188:189], 1, v[108:109]
	global_store_dwordx4 v[108:109], v[114:117], off
.LBB0_1181:
	s_or_b64 exec, exec, s[22:23]
	v_pk_fma_f32 v[108:109], v[54:55], v[128:129], v[124:125]
	v_pk_fma_f32 v[112:113], v[60:61], v[126:127], v[122:123]
	v_pk_fma_f32 v[58:59], v[58:59], v[102:103], v[108:109]
	s_waitcnt lgkmcnt(0)
	v_cndmask_b32_e64 v114, v78, v138, s[44:45]
	v_pk_fma_f32 v[58:59], v[62:63], v[120:121], v[58:59]
	v_cndmask_b32_e64 v115, v94, v139, s[44:45]
	v_cndmask_b32_e64 v78, v95, v140, s[44:45]
	v_exp_f32_e64 v105, -v58
	v_exp_f32_e64 v109, -v59
	v_pk_fma_f32 v[94:95], v[52:53], v[126:127], v[122:123]
	v_pk_fma_f32 v[52:53], v[52:53], v[100:101], v[112:113]
	v_add_f32_e32 v105, 1.0, v105
	v_pk_fma_f32 v[52:53], v[44:45], v[118:119], v[52:53]
	v_pk_fma_f32 v[56:57], v[56:57], v[100:101], v[94:95]
	v_rcp_f32_e32 v108, v105
	v_add_f32_e32 v105, 1.0, v109
	v_pk_fma_f32 v[56:57], v[60:61], v[118:119], v[56:57]
	v_exp_f32_e64 v112, -v52
	v_exp_f32_e64 v113, -v53
	v_exp_f32_e64 v94, -v56
	v_exp_f32_e64 v95, -v57
	v_rcp_f32_e32 v109, v105
	v_add_f32_e32 v105, 1.0, v112
	v_rcp_f32_e32 v116, v105
	v_add_f32_e32 v105, 1.0, v113
	v_pk_fma_f32 v[112:113], v[62:63], v[128:129], v[124:125]
	v_add_f32_e32 v94, 1.0, v94
	v_pk_fma_f32 v[54:55], v[54:55], v[102:103], v[112:113]
	v_add_f32_e32 v95, 1.0, v95
	v_pk_fma_f32 v[54:55], v[46:47], v[120:121], v[54:55]
	v_pk_fma_f32 v[44:45], v[44:45], v[126:127], v[122:123]
	v_rcp_f32_e32 v94, v94
	v_rcp_f32_e32 v95, v95
	v_cndmask_b32_e64 v75, v75, v131, s[44:45]
	v_cndmask_b32_e64 v74, v74, v130, s[44:45]
	v_pk_fma_f32 v[44:45], v[60:61], v[100:101], v[44:45]
	v_pk_fma_f32 v[46:47], v[46:47], v[128:129], v[124:125]
	v_pk_fma_f32 v[44:45], v[118:119], v[74:75], v[44:45]
	v_cndmask_b32_e64 v71, v71, v133, s[44:45]
	v_cndmask_b32_e64 v70, v70, v132, s[44:45]
	v_pk_fma_f32 v[46:47], v[62:63], v[102:103], v[46:47]
	v_pk_fma_f32 v[74:75], v[36:37], v[90:91], v[66:67]
	v_exp_f32_e64 v112, -v54
	v_pk_fma_f32 v[46:47], v[120:121], v[70:71], v[46:47]
	v_pk_fma_f32 v[70:71], v[38:39], v[92:93], v[68:69]
	v_pk_fma_f32 v[40:41], v[40:41], v[86:87], v[74:75]
	v_exp_f32_e64 v113, -v55
	v_pk_fma_f32 v[42:43], v[42:43], v[88:89], v[70:71]
	v_pk_fma_f32 v[40:41], v[48:49], v[82:83], v[40:41]
	v_pk_fma_f32 v[42:43], v[50:51], v[84:85], v[42:43]
	v_pk_mul_f32 v[56:57], v[56:57], v[94:95]
	v_pk_mul_f32 v[58:59], v[58:59], v[108:109]
	v_pk_mul_f32 v[40:41], v[56:57], v[40:41]
	v_rcp_f32_e32 v117, v105
	v_add_f32_e32 v105, 1.0, v112
	v_pk_mul_f32 v[42:43], v[58:59], v[42:43]
	v_cvt_pk_bf16_f32 v112, v40, v41
	v_or_b32_e32 v40, 1, v194
	v_rcp_f32_e32 v134, v105
	v_add_f32_e32 v105, 1.0, v113
	v_cvt_pk_bf16_f32 v113, v42, v43
	v_add_u32_e32 v42, s2, v40
	v_mov_b64_e32 v[40:41], s[88:89]
	v_mad_i64_i32 v[42:43], s[22:23], v42, s3, v[40:41]
	v_lshlrev_b64 v[70:71], 1, v[188:189]
	v_pk_fma_f32 v[56:57], v[48:49], v[90:91], v[66:67]
	v_lshl_add_u64 v[42:43], v[42:43], 0, v[70:71]
	v_pk_fma_f32 v[36:37], v[36:37], v[86:87], v[56:57]
	global_store_dwordx4 v[42:43], v[110:113], off
	v_pk_fma_f32 v[42:43], v[50:51], v[92:93], v[68:69]
	v_pk_fma_f32 v[36:37], v[32:33], v[82:83], v[36:37]
	v_exp_f32_e64 v60, -v44
	v_exp_f32_e64 v61, -v45
	v_exp_f32_e64 v62, -v46
	v_exp_f32_e64 v63, -v47
	v_pk_fma_f32 v[38:39], v[38:39], v[88:89], v[42:43]
	v_pk_mul_f32 v[42:43], v[52:53], v[116:117]
	v_rcp_f32_e32 v135, v105
	v_pk_mul_f32 v[36:37], v[42:43], v[36:37]
	v_add_f32_e32 v60, 1.0, v60
	v_cvt_pk_bf16_f32 v108, v36, v37
	v_or_b32_e32 v36, 2, v194
	v_add_u32_e32 v36, s2, v36
	v_add_f32_e32 v61, 1.0, v61
	v_add_f32_e32 v62, 1.0, v62
	v_add_f32_e32 v63, 1.0, v63
	v_pk_fma_f32 v[38:39], v[34:35], v[84:85], v[38:39]
	v_mad_i64_i32 v[36:37], s[22:23], v36, s3, v[40:41]
	v_rcp_f32_e32 v60, v60
	v_rcp_f32_e32 v61, v61
	v_rcp_f32_e32 v62, v62
	v_rcp_f32_e32 v63, v63
	v_pk_mul_f32 v[52:53], v[54:55], v[134:135]
	v_lshl_add_u64 v[36:37], v[36:37], 0, v[70:71]
	v_pk_mul_f32 v[38:39], v[52:53], v[38:39]
	v_pk_fma_f32 v[34:35], v[34:35], v[92:93], v[68:69]
	v_cvt_pk_bf16_f32 v109, v38, v39
	global_store_dwordx4 v[36:37], v[106:109], off
	v_pk_fma_f32 v[32:33], v[32:33], v[90:91], v[66:67]
	v_cndmask_b32_e64 v79, v79, v141, s[44:45]
	v_pk_fma_f32 v[34:35], v[50:51], v[88:89], v[34:35]
	v_pk_fma_f32 v[32:33], v[48:49], v[86:87], v[32:33]
	v_pk_fma_f32 v[34:35], v[84:85], v[78:79], v[34:35]
	v_pk_fma_f32 v[32:33], v[82:83], v[114:115], v[32:33]
	v_pk_mul_f32 v[36:37], v[44:45], v[60:61]
	v_pk_mul_f32 v[38:39], v[46:47], v[62:63]
	v_pk_mul_f32 v[32:33], v[36:37], v[32:33]
	v_pk_mul_f32 v[34:35], v[38:39], v[34:35]
	v_cvt_pk_bf16_f32 v100, v32, v33
	s_nop 0
	v_cvt_pk_bf16_f32 v101, v34, v35
	s_and_saveexec_b64 s[22:23], s[52:53]
	s_cbranch_execz .LBB0_1183
	v_or_b32_e32 v32, 3, v194
	v_add_u32_e32 v34, s2, v32
	v_mov_b64_e32 v[32:33], s[88:89]
	v_mad_i64_i32 v[32:33], s[34:35], v34, s3, v[32:33]
	v_lshl_add_u64 v[32:33], v[188:189], 1, v[32:33]
	global_store_dwordx4 v[32:33], v[98:101], off

.LBB0_1185:
	v_mov_b32_dpp v78, v24 row_ror:15 row_mask:0xf bank_mask:0xf
	v_mov_b32_dpp v79, v25 row_ror:15 row_mask:0xf bank_mask:0xf
	v_mov_b32_dpp v82, v22 row_ror:1 row_mask:0xf bank_mask:0xf
	v_mov_b32_dpp v74, v26 row_ror:15 row_mask:0xf bank_mask:0xf
	v_mov_b32_dpp v83, v23 row_ror:1 row_mask:0xf bank_mask:0xf
	v_mov_b32_dpp v75, v27 row_ror:15 row_mask:0xf bank_mask:0xf
	ds_read_b128 v[40:43], v223 offset:9744
	ds_read_b128 v[36:39], v223 offset:10768
	ds_read_b128 v[32:35], v223 offset:11792
	ds_read_b128 v[44:47], v223 offset:8720
	ds_read_b128 v[88:91], v221 offset:304
	s_and_b64 vcc, exec, s[60:61]
	v_mov_b32_e32 v85, 0
	v_mov_b32_e32 v86, 0
	v_mov_b32_e32 v87, 0
	s_cbranch_vccnz .LBB0_1187
	ds_read_b128 v[84:87], v104 offset:48
.LBB0_1187:
	s_waitcnt lgkmcnt(5)
	v_mov_b32_dpp v93, v21 row_shr:1 row_mask:0xf bank_mask:0xf
	v_mov_b32_dpp v92, v20 row_shr:1 row_mask:0xf bank_mask:0xf
	v_pk_fma_f32 v[92:93], v[60:61], v[92:93], v[52:53]
	v_cndmask_b32_e64 v83, v83, v95, s[48:49]
	v_pk_fma_f32 v[92:93], v[24:25], v[56:57], v[92:93]
	v_cndmask_b32_e64 v82, v82, v94, s[48:49]
	v_pk_fma_f32 v[98:99], v[28:29], v[48:49], v[92:93]
	v_pk_fma_f32 v[82:83], v[62:63], v[82:83], v[54:55]
	v_pk_fma_f32 v[82:83], v[26:27], v[58:59], v[82:83]
	v_exp_f32_e64 v92, -v98
	v_exp_f32_e64 v93, -v99
	v_pk_fma_f32 v[82:83], v[30:31], v[50:51], v[82:83]
	v_add_f32_e32 v92, 1.0, v92
	v_rcp_f32_e32 v100, v92
	v_add_f32_e32 v92, 1.0, v93
	v_exp_f32_e64 v93, -v82
	v_rcp_f32_e32 v101, v92
	v_exp_f32_e64 v95, -v83
	v_add_f32_e32 v92, 1.0, v93
	v_rcp_f32_e32 v94, v92
	v_mov_b32_dpp v93, v4 row_ror:1 row_mask:0xf bank_mask:0xf
	s_waitcnt lgkmcnt(0)
	v_cndmask_b32_e64 v102, v93, v88, s[48:49]
	v_add_f32_e32 v92, 1.0, v95
	v_mov_b32_dpp v88, v5 row_ror:1 row_mask:0xf bank_mask:0xf
	v_cndmask_b32_e64 v103, v88, v89, s[48:49]
	v_rcp_f32_e32 v95, v92
	v_mov_b32_dpp v91, v7 row_shr:1 row_mask:0xf bank_mask:0xf
	v_mov_b32_dpp v90, v6 row_shr:1 row_mask:0xf bank_mask:0xf
	v_pk_fma_f32 v[90:91], v[46:47], v[90:91], v[34:35]
	v_pk_fma_f32 v[102:103], v[44:45], v[102:103], v[32:33]
	v_pk_fma_f32 v[90:91], v[14:15], v[42:43], v[90:91]
	v_pk_fma_f32 v[102:103], v[12:13], v[40:41], v[102:103]
	v_pk_fma_f32 v[90:91], v[10:11], v[38:39], v[90:91]
	v_pk_fma_f32 v[102:103], v[8:9], v[36:37], v[102:103]
	v_pk_mul_f32 v[98:99], v[98:99], v[100:101]
	v_pk_mul_f32 v[82:83], v[82:83], v[94:95]
	v_mov_b32_dpp v92, v12 row_ror:15 row_mask:0xf bank_mask:0xf
	v_mov_b32_dpp v93, v13 row_ror:15 row_mask:0xf bank_mask:0xf
	v_mov_b32_dpp v89, v14 row_ror:15 row_mask:0xf bank_mask:0xf
	v_mov_b32_dpp v88, v15 row_ror:15 row_mask:0xf bank_mask:0xf
	v_pk_mul_f32 v[90:91], v[82:83], v[90:91]
	v_pk_mul_f32 v[82:83], v[98:99], v[102:103]
	s_nop 0
	v_cvt_pk_bf16_f32 v82, v82, v83
	v_cvt_pk_bf16_f32 v83, v90, v91
	s_and_saveexec_b64 s[22:23], s[54:55]
	s_cbranch_execz .LBB0_1189
	v_add_u32_e32 v90, 0x80, v194
	v_add_u32_e32 v94, s2, v90
	v_mov_b64_e32 v[90:91], s[88:89]
	v_mad_i64_i32 v[90:91], s[34:35], v94, s3, v[90:91]
	v_lshl_add_u64 v[90:91], v[188:189], 1, v[90:91]
	global_store_dwordx4 v[90:91], v[80:83], off
.LBB0_1189:
	s_or_b64 exec, exec, s[22:23]
	s_nop 0
	v_cndmask_b32_e64 v80, v92, v84, s[44:45]
	v_cndmask_b32_e64 v81, v93, v85, s[44:45]
	v_pk_fma_f32 v[84:85], v[28:29], v[56:57], v[52:53]
	v_cndmask_b32_e64 v82, v89, v86, s[44:45]
	v_pk_fma_f32 v[24:25], v[24:25], v[60:61], v[84:85]
	v_pk_fma_f32 v[90:91], v[18:19], v[58:59], v[54:55]
	v_pk_fma_f32 v[24:25], v[16:17], v[48:49], v[24:25]
	v_cndmask_b32_e64 v66, v78, v66, s[44:45]
	v_cndmask_b32_e64 v67, v79, v67, s[44:45]
	v_exp_f32_e64 v84, -v24
	v_exp_f32_e64 v85, -v25
	v_cndmask_b32_e64 v83, v88, v87, s[44:45]
	v_pk_fma_f32 v[86:87], v[30:31], v[58:59], v[54:55]
	v_pk_fma_f32 v[88:89], v[16:17], v[56:57], v[52:53]
	v_pk_fma_f32 v[26:27], v[26:27], v[62:63], v[86:87]
	v_pk_fma_f32 v[28:29], v[28:29], v[60:61], v[88:89]
	v_pk_fma_f32 v[26:27], v[18:19], v[50:51], v[26:27]
	v_pk_fma_f32 v[28:29], v[20:21], v[48:49], v[28:29]
	v_pk_fma_f32 v[30:31], v[30:31], v[62:63], v[90:91]
	v_exp_f32_e64 v86, -v26
	v_exp_f32_e64 v87, -v27
	v_pk_fma_f32 v[20:21], v[20:21], v[56:57], v[52:53]
	v_add_f32_e32 v84, 1.0, v84
	v_add_f32_e32 v85, 1.0, v85
	v_pk_fma_f32 v[30:31], v[22:23], v[50:51], v[30:31]
	v_pk_fma_f32 v[16:17], v[16:17], v[60:61], v[20:21]
	v_pk_fma_f32 v[22:23], v[22:23], v[58:59], v[54:55]
	v_rcp_f32_e32 v84, v84
	v_rcp_f32_e32 v85, v85
	v_add_f32_e32 v86, 1.0, v86
	v_add_f32_e32 v87, 1.0, v87
	v_pk_fma_f32 v[16:17], v[48:49], v[66:67], v[16:17]
	v_cndmask_b32_e64 v48, v74, v68, s[44:45]
	v_cndmask_b32_e64 v49, v75, v69, s[44:45]
	v_pk_fma_f32 v[18:19], v[18:19], v[62:63], v[22:23]
	v_rcp_f32_e32 v86, v86
	v_rcp_f32_e32 v87, v87
	v_pk_fma_f32 v[18:19], v[50:51], v[48:49], v[18:19]
	v_pk_fma_f32 v[50:51], v[8:9], v[40:41], v[32:33]
	v_exp_f32_e64 v88, -v28
	v_exp_f32_e64 v89, -v29
	v_pk_fma_f32 v[48:49], v[10:11], v[42:43], v[34:35]
	v_pk_fma_f32 v[12:13], v[12:13], v[44:45], v[50:51]
	v_pk_fma_f32 v[14:15], v[14:15], v[46:47], v[48:49]
	v_pk_fma_f32 v[12:13], v[0:1], v[36:37], v[12:13]
	v_pk_fma_f32 v[14:15], v[2:3], v[38:39], v[14:15]
	v_pk_mul_f32 v[24:25], v[24:25], v[84:85]
	v_pk_mul_f32 v[26:27], v[26:27], v[86:87]
	v_pk_mul_f32 v[12:13], v[24:25], v[12:13]
	v_add_f32_e32 v88, 1.0, v88
	v_add_f32_e32 v89, 1.0, v89
	v_exp_f32_e64 v90, -v30
	v_exp_f32_e64 v91, -v31
	v_pk_mul_f32 v[14:15], v[26:27], v[14:15]
	v_cvt_pk_bf16_f32 v78, v12, v13
	v_add_u32_e32 v12, 0x81, v194
	v_rcp_f32_e32 v88, v88
	v_rcp_f32_e32 v89, v89
	v_cvt_pk_bf16_f32 v79, v14, v15
	v_add_u32_e32 v14, s2, v12
	v_mov_b64_e32 v[12:13], s[88:89]
	v_mad_i64_i32 v[14:15], s[22:23], v14, s3, v[12:13]
	v_pk_fma_f32 v[24:25], v[0:1], v[40:41], v[32:33]
	v_lshl_add_u64 v[14:15], v[14:15], 0, v[70:71]
	v_pk_fma_f32 v[8:9], v[8:9], v[44:45], v[24:25]
	v_add_f32_e32 v90, 1.0, v90
	v_add_f32_e32 v91, 1.0, v91
	v_exp_f32_e64 v20, -v16
	v_exp_f32_e64 v21, -v17
	v_exp_f32_e64 v22, -v18
	v_exp_f32_e64 v23, -v19
	global_store_dwordx4 v[14:15], v[76:79], off
	v_pk_fma_f32 v[14:15], v[2:3], v[42:43], v[34:35]
	v_pk_fma_f32 v[8:9], v[4:5], v[36:37], v[8:9]
	v_rcp_f32_e32 v90, v90
	v_rcp_f32_e32 v91, v91
	v_pk_fma_f32 v[10:11], v[10:11], v[46:47], v[14:15]
	v_pk_mul_f32 v[14:15], v[28:29], v[88:89]
	v_add_f32_e32 v20, 1.0, v20
	v_pk_mul_f32 v[8:9], v[14:15], v[8:9]
	v_add_f32_e32 v21, 1.0, v21
	v_cvt_pk_bf16_f32 v74, v8, v9
	v_add_u32_e32 v8, s2, v195
	v_add_f32_e32 v22, 1.0, v22
	v_add_f32_e32 v23, 1.0, v23
	v_pk_fma_f32 v[10:11], v[6:7], v[38:39], v[10:11]
	v_mad_i64_i32 v[8:9], s[22:23], v8, s3, v[12:13]
	v_rcp_f32_e32 v20, v20
	v_rcp_f32_e32 v21, v21
	v_rcp_f32_e32 v22, v22
	v_rcp_f32_e32 v23, v23
	v_pk_mul_f32 v[24:25], v[30:31], v[90:91]
	v_lshl_add_u64 v[8:9], v[8:9], 0, v[70:71]
	v_pk_mul_f32 v[10:11], v[24:25], v[10:11]
	v_pk_fma_f32 v[6:7], v[6:7], v[42:43], v[34:35]
	v_cvt_pk_bf16_f32 v75, v10, v11
	global_store_dwordx4 v[8:9], v[72:75], off
	v_pk_fma_f32 v[4:5], v[4:5], v[40:41], v[32:33]
	v_pk_fma_f32 v[2:3], v[2:3], v[46:47], v[6:7]
	v_pk_fma_f32 v[0:1], v[0:1], v[44:45], v[4:5]
	v_pk_fma_f32 v[2:3], v[38:39], v[82:83], v[2:3]
	v_pk_fma_f32 v[0:1], v[36:37], v[80:81], v[0:1]
	v_pk_mul_f32 v[4:5], v[16:17], v[20:21]
	v_pk_mul_f32 v[6:7], v[18:19], v[22:23]
	v_pk_mul_f32 v[0:1], v[4:5], v[0:1]
	v_pk_mul_f32 v[2:3], v[6:7], v[2:3]
	v_cvt_pk_bf16_f32 v66, v0, v1
	s_nop 0
	v_cvt_pk_bf16_f32 v67, v2, v3
	s_and_saveexec_b64 s[22:23], s[56:57]
	s_cbranch_execz .LBB0_1191
	v_add_u32_e32 v2, s2, v214
	v_mov_b64_e32 v[0:1], s[88:89]
	v_mad_i64_i32 v[0:1], s[2:3], v2, s3, v[0:1]
	v_lshl_add_u64 v[0:1], v[188:189], 1, v[0:1]
	global_store_dwordx4 v[0:1], v[64:67], off

	.amdhsa_kernel _Z8mega_fwd4Args
		.amdhsa_group_segment_fixed_size 0
		.amdhsa_private_segment_fixed_size 0
		.amdhsa_kernarg_size 520
		.amdhsa_user_sgpr_count 2
		.amdhsa_user_sgpr_dispatch_ptr 0
		.amdhsa_user_sgpr_queue_ptr 0
		.amdhsa_user_sgpr_kernarg_segment_ptr 1
		.amdhsa_user_sgpr_dispatch_id 0
		.amdhsa_user_sgpr_kernarg_preload_length 0
		.amdhsa_user_sgpr_kernarg_preload_offset 0
		.amdhsa_user_sgpr_private_segment_size 0
		.amdhsa_uses_dynamic_stack 0
		.amdhsa_enable_private_segment 0
		.amdhsa_system_sgpr_workgroup_id_x 1
		.amdhsa_system_sgpr_workgroup_id_y 0
		.amdhsa_system_sgpr_workgroup_id_z 0
		.amdhsa_system_sgpr_workgroup_info 0
		.amdhsa_system_vgpr_workitem_id 0
		.amdhsa_next_free_vgpr 256
		.amdhsa_next_free_sgpr 102
		.amdhsa_accum_offset 256
		.amdhsa_reserve_vcc 1
		.amdhsa_float_round_mode_32 0
		.amdhsa_float_round_mode_16_64 0
		.amdhsa_float_denorm_mode_32 3
		.amdhsa_float_denorm_mode_16_64 3
		.amdhsa_dx10_clamp 1
		.amdhsa_ieee_mode 1
		.amdhsa_fp16_overflow 0
		.amdhsa_tg_split 0
		.amdhsa_exception_fp_ieee_invalid_op 0
		.amdhsa_exception_fp_denorm_src 0
		.amdhsa_exception_fp_ieee_div_zero 0
		.amdhsa_exception_fp_ieee_overflow 0
		.amdhsa_exception_fp_ieee_underflow 0
		.amdhsa_exception_fp_ieee_inexact 0
		.amdhsa_exception_int_div_zero 0
	.end_amdhsa_kernel

amdhsa.kernels:
  - .agpr_count:     0
    .args:
      - .offset:         0
        .size:           264
        .value_kind:     by_value
      - .offset:         264
        .size:           4
        .value_kind:     hidden_block_count_x
      - .offset:         268
        .size:           4
        .value_kind:     hidden_block_count_y
      - .offset:         272
        .size:           4
        .value_kind:     hidden_block_count_z
      - .offset:         276
        .size:           2
        .value_kind:     hidden_group_size_x
      - .offset:         278
        .size:           2
        .value_kind:     hidden_group_size_y
      - .offset:         280
        .size:           2
        .value_kind:     hidden_group_size_z
      - .offset:         282
        .size:           2
        .value_kind:     hidden_remainder_x
      - .offset:         284
        .size:           2
        .value_kind:     hidden_remainder_y
      - .offset:         286
        .size:           2
        .value_kind:     hidden_remainder_z
      - .offset:         304
        .size:           8
        .value_kind:     hidden_global_offset_x
      - .offset:         312
        .size:           8
        .value_kind:     hidden_global_offset_y
      - .offset:         320
        .size:           8
        .value_kind:     hidden_global_offset_z
      - .offset:         328
        .size:           2
        .value_kind:     hidden_grid_dims
      - .offset:         384
        .size:           4
        .value_kind:     hidden_dynamic_lds_size
    .group_segment_fixed_size: 0
    .kernarg_segment_align: 8
    .kernarg_segment_size: 520
    .language:       OpenCL C
    .language_version:
      - 2
      - 0
    .max_flat_workgroup_size: 512
    .name:           _Z8mega_fwd4Args
    .private_segment_fixed_size: 0
    .sgpr_count:     108
    .sgpr_spill_count: 337
    .symbol:         _Z8mega_fwd4Args.kd
    .uniform_work_group_size: 1
    .uses_dynamic_stack: false
    .vgpr_count:     256
    .vgpr_spill_count: 0
    .wavefront_size: 64
